# v77: v68 + priority 3 while the gather loop issues its 32 row loads, priority 0 for the conversion/FMA part
# baseline (speedup 1.0000x reference)
.Lprio_base_done:
.LBB0_870:
	s_setprio 3
	v_add_u32_e32 v0, s1, v199
	ds_read_b128 v[2:5], v0
	ds_read_b128 v[6:9], v0 offset:16
	ds_read_b128 v[14:17], v0 offset:32
	ds_read_b128 v[26:29], v0 offset:48
	s_waitcnt lgkmcnt(3)
	v_readfirstlane_b32 s20, v2
	s_lshl_b64 s[42:43], s[20:21], 11
	v_lshl_add_u64 v[22:23], v[140:141], 0, s[42:43]
	global_load_dwordx4 v[126:129], v[22:23], off
	v_readfirstlane_b32 s20, v3
	s_lshl_b64 s[42:43], s[20:21], 11
	v_lshl_add_u64 v[24:25], v[140:141], 0, s[42:43]
	global_load_dwordx4 v[122:125], v[24:25], off
	v_readfirstlane_b32 s20, v4
	s_lshl_b64 s[42:43], s[20:21], 11
	v_lshl_add_u64 v[20:21], v[140:141], 0, s[42:43]
	global_load_dwordx4 v[118:121], v[20:21], off
	v_readfirstlane_b32 s20, v5
	s_lshl_b64 s[42:43], s[20:21], 11
	s_waitcnt lgkmcnt(2)
	v_readfirstlane_b32 s20, v6
	v_lshl_add_u64 v[18:19], v[140:141], 0, s[42:43]
	s_lshl_b64 s[42:43], s[20:21], 11
	v_readfirstlane_b32 s20, v7
	v_lshl_add_u64 v[10:11], v[140:141], 0, s[42:43]
	s_lshl_b64 s[42:43], s[20:21], 11
	v_readfirstlane_b32 s20, v8
	v_lshl_add_u64 v[2:3], v[140:141], 0, s[42:43]
	s_lshl_b64 s[42:43], s[20:21], 11
	v_readfirstlane_b32 s20, v9
	v_lshl_add_u64 v[4:5], v[140:141], 0, s[42:43]
	s_lshl_b64 s[42:43], s[20:21], 11
	s_waitcnt lgkmcnt(1)
	v_readfirstlane_b32 s20, v14
	v_lshl_add_u64 v[6:7], v[140:141], 0, s[42:43]
	s_lshl_b64 s[42:43], s[20:21], 11
	v_readfirstlane_b32 s20, v15
	global_load_dwordx4 v[114:117], v[18:19], off
	v_lshl_add_u64 v[8:9], v[140:141], 0, s[42:43]
	s_lshl_b64 s[42:43], s[20:21], 11
	v_readfirstlane_b32 s20, v16
	v_lshl_add_u64 v[12:13], v[140:141], 0, s[42:43]
	s_lshl_b64 s[42:43], s[20:21], 11
	v_readfirstlane_b32 s20, v17
	v_lshl_add_u64 v[14:15], v[140:141], 0, s[42:43]
	s_lshl_b64 s[42:43], s[20:21], 11
	s_waitcnt lgkmcnt(0)
	v_readfirstlane_b32 s20, v26
	v_lshl_add_u64 v[16:17], v[140:141], 0, s[42:43]
	s_lshl_b64 s[42:43], s[20:21], 11
	v_readfirstlane_b32 s20, v27
	v_lshl_add_u64 v[188:189], v[140:141], 0, s[42:43]
	s_lshl_b64 s[42:43], s[20:21], 11
	v_readfirstlane_b32 s20, v28
	v_lshl_add_u64 v[190:191], v[140:141], 0, s[42:43]
	s_lshl_b64 s[42:43], s[20:21], 11
	v_readfirstlane_b32 s20, v29
	v_lshl_add_u64 v[192:193], v[140:141], 0, s[42:43]
	s_lshl_b64 s[42:43], s[20:21], 11
	v_lshl_add_u64 v[194:195], v[140:141], 0, s[42:43]
	global_load_dwordx4 v[110:113], v[10:11], off
	global_load_dwordx4 v[90:93], v[12:13], off
	global_load_dwordx4 v[106:109], v[2:3], off
	global_load_dwordx4 v[102:105], v[4:5], off
	global_load_dwordx4 v[98:101], v[6:7], off
	global_load_dwordx4 v[94:97], v[8:9], off
	global_load_dwordx4 v[86:89], v[14:15], off
	global_load_dwordx4 v[82:85], v[16:17], off
	global_load_dwordx4 v[78:81], v[188:189], off
	global_load_dwordx4 v[74:77], v[190:191], off
	global_load_dwordx4 v[70:73], v[192:193], off
	global_load_dwordx4 v[66:69], v[194:195], off
	global_load_dwordx4 v[62:65], v[22:23], off offset:1024
	global_load_dwordx4 v[58:61], v[24:25], off offset:1024
	global_load_dwordx4 v[54:57], v[20:21], off offset:1024
	global_load_dwordx4 v[50:53], v[18:19], off offset:1024
	global_load_dwordx4 v[46:49], v[10:11], off offset:1024
	global_load_dwordx4 v[42:45], v[2:3], off offset:1024
	global_load_dwordx4 v[38:41], v[4:5], off offset:1024
	global_load_dwordx4 v[34:37], v[6:7], off offset:1024
	global_load_dwordx4 v[30:33], v[8:9], off offset:1024
	global_load_dwordx4 v[26:29], v[12:13], off offset:1024
	global_load_dwordx4 v[22:25], v[14:15], off offset:1024
	global_load_dwordx4 v[18:21], v[16:17], off offset:1024
	s_nop 0
	global_load_dwordx4 v[14:17], v[188:189], off offset:1024
	global_load_dwordx4 v[10:13], v[190:191], off offset:1024
	global_load_dwordx4 v[6:9], v[192:193], off offset:1024
	global_load_dwordx4 v[2:5], v[194:195], off offset:1024
	s_setprio 0
	s_waitcnt vmcnt(31)
	v_cvt_pk_f32_fp8_e32 v[188:189], v126
	v_cvt_pk_f32_fp8_sdwa v[190:191], v126 src0_sel:WORD_1
	v_pk_fma_f32 v[188:189], v[188:189], v[154:155], 0 op_sel_hi:[1,1,0]
	s_nop 0
	v_pk_fma_f32 v[188:189], v[190:191], v[156:157], v[188:189]
	v_cvt_pk_f32_fp8_e32 v[190:191], v127
	v_cvt_pk_f32_fp8_sdwa v[126:127], v127 src0_sel:WORD_1
	v_pk_fma_f32 v[188:189], v[190:191], v[158:159], v[188:189]
	s_nop 0
	v_pk_fma_f32 v[126:127], v[126:127], v[162:163], v[188:189]
	v_cvt_pk_f32_fp8_e32 v[188:189], v128
	v_pk_fma_f32 v[126:127], v[188:189], v[164:165], v[126:127]
	v_cvt_pk_f32_fp8_sdwa v[188:189], v128 src0_sel:WORD_1
	v_pk_fma_f32 v[126:127], v[188:189], v[166:167], v[126:127]
	v_cvt_pk_f32_fp8_e32 v[188:189], v129
	v_cvt_pk_f32_fp8_sdwa v[128:129], v129 src0_sel:WORD_1
	v_pk_fma_f32 v[126:127], v[188:189], v[168:169], v[126:127]
	s_nop 0
	v_pk_fma_f32 v[126:127], v[128:129], v[170:171], v[126:127]
	s_waitcnt vmcnt(30)
	v_cvt_pk_f32_fp8_sdwa v[128:129], v122 src0_sel:WORD_1
	v_add_f32_e32 v0, v126, v127
	v_cvt_pk_f32_fp8_e32 v[126:127], v122
	v_pk_fma_f32 v[126:127], v[126:127], v[154:155], 0 op_sel_hi:[1,1,0]
	s_nop 0
	v_pk_fma_f32 v[126:127], v[128:129], v[156:157], v[126:127]
	v_cvt_pk_f32_fp8_e32 v[128:129], v123
	v_cvt_pk_f32_fp8_sdwa v[122:123], v123 src0_sel:WORD_1
	v_pk_fma_f32 v[126:127], v[128:129], v[158:159], v[126:127]
	s_nop 0
	v_pk_fma_f32 v[122:123], v[122:123], v[162:163], v[126:127]
	v_cvt_pk_f32_fp8_e32 v[126:127], v124
	v_pk_fma_f32 v[122:123], v[126:127], v[164:165], v[122:123]
	v_cvt_pk_f32_fp8_sdwa v[126:127], v124 src0_sel:WORD_1
	v_pk_fma_f32 v[122:123], v[126:127], v[166:167], v[122:123]
	v_cvt_pk_f32_fp8_e32 v[126:127], v125
	v_cvt_pk_f32_fp8_sdwa v[124:125], v125 src0_sel:WORD_1
	v_pk_fma_f32 v[122:123], v[126:127], v[168:169], v[122:123]
	s_nop 0
	v_pk_fma_f32 v[122:123], v[124:125], v[170:171], v[122:123]
	s_waitcnt vmcnt(29)
	v_cvt_pk_f32_fp8_sdwa v[124:125], v118 src0_sel:WORD_1
	v_add_f32_e32 v126, v122, v123
	v_cvt_pk_f32_fp8_e32 v[122:123], v118
	v_pk_fma_f32 v[122:123], v[122:123], v[154:155], 0 op_sel_hi:[1,1,0]
	s_nop 0
	v_pk_fma_f32 v[122:123], v[124:125], v[156:157], v[122:123]
	v_cvt_pk_f32_fp8_e32 v[124:125], v119
	v_cvt_pk_f32_fp8_sdwa v[118:119], v119 src0_sel:WORD_1
	v_pk_fma_f32 v[122:123], v[124:125], v[158:159], v[122:123]
	s_nop 0
	v_pk_fma_f32 v[118:119], v[118:119], v[162:163], v[122:123]
	v_cvt_pk_f32_fp8_e32 v[122:123], v120
	v_pk_fma_f32 v[118:119], v[122:123], v[164:165], v[118:119]
	v_cvt_pk_f32_fp8_sdwa v[122:123], v120 src0_sel:WORD_1
	v_pk_fma_f32 v[118:119], v[122:123], v[166:167], v[118:119]
	v_cvt_pk_f32_fp8_e32 v[122:123], v121
	v_cvt_pk_f32_fp8_sdwa v[120:121], v121 src0_sel:WORD_1
	v_pk_fma_f32 v[118:119], v[122:123], v[168:169], v[118:119]
	s_nop 0
	v_pk_fma_f32 v[118:119], v[120:121], v[170:171], v[118:119]
	s_waitcnt vmcnt(28)
	v_cvt_pk_f32_fp8_sdwa v[120:121], v114 src0_sel:WORD_1
	v_add_f32_e32 v122, v118, v119
	v_cvt_pk_f32_fp8_e32 v[118:119], v114
	v_pk_fma_f32 v[118:119], v[118:119], v[154:155], 0 op_sel_hi:[1,1,0]
	s_nop 0
	v_pk_fma_f32 v[118:119], v[120:121], v[156:157], v[118:119]
	v_cvt_pk_f32_fp8_e32 v[120:121], v115
	v_cvt_pk_f32_fp8_sdwa v[114:115], v115 src0_sel:WORD_1
	v_pk_fma_f32 v[118:119], v[120:121], v[158:159], v[118:119]
	s_nop 0
	v_pk_fma_f32 v[114:115], v[114:115], v[162:163], v[118:119]
	v_cvt_pk_f32_fp8_e32 v[118:119], v116
	v_pk_fma_f32 v[114:115], v[118:119], v[164:165], v[114:115]
	v_cvt_pk_f32_fp8_sdwa v[118:119], v116 src0_sel:WORD_1
	v_pk_fma_f32 v[114:115], v[118:119], v[166:167], v[114:115]
	v_cvt_pk_f32_fp8_e32 v[118:119], v117
	v_cvt_pk_f32_fp8_sdwa v[116:117], v117 src0_sel:WORD_1
	v_pk_fma_f32 v[114:115], v[118:119], v[168:169], v[114:115]
	s_nop 0
	v_pk_fma_f32 v[114:115], v[116:117], v[170:171], v[114:115]
	s_waitcnt vmcnt(27)
	v_cvt_pk_f32_fp8_sdwa v[116:117], v110 src0_sel:WORD_1
	v_add_f32_e32 v118, v114, v115
	v_cvt_pk_f32_fp8_e32 v[114:115], v110
	v_pk_fma_f32 v[114:115], v[114:115], v[154:155], 0 op_sel_hi:[1,1,0]
	s_nop 0
	v_pk_fma_f32 v[114:115], v[116:117], v[156:157], v[114:115]
	v_cvt_pk_f32_fp8_e32 v[116:117], v111
	v_cvt_pk_f32_fp8_sdwa v[110:111], v111 src0_sel:WORD_1
	v_pk_fma_f32 v[114:115], v[116:117], v[158:159], v[114:115]
	s_nop 0
	v_pk_fma_f32 v[110:111], v[110:111], v[162:163], v[114:115]
	v_cvt_pk_f32_fp8_e32 v[114:115], v112
	v_pk_fma_f32 v[110:111], v[114:115], v[164:165], v[110:111]
	v_cvt_pk_f32_fp8_sdwa v[114:115], v112 src0_sel:WORD_1
	v_pk_fma_f32 v[110:111], v[114:115], v[166:167], v[110:111]
	v_cvt_pk_f32_fp8_e32 v[114:115], v113
	v_cvt_pk_f32_fp8_sdwa v[112:113], v113 src0_sel:WORD_1
	v_pk_fma_f32 v[110:111], v[114:115], v[168:169], v[110:111]
	s_nop 0
	v_pk_fma_f32 v[110:111], v[112:113], v[170:171], v[110:111]
	s_waitcnt vmcnt(25)
	v_cvt_pk_f32_fp8_sdwa v[112:113], v106 src0_sel:WORD_1
	v_add_f32_e32 v114, v110, v111
	v_cvt_pk_f32_fp8_e32 v[110:111], v106
	v_pk_fma_f32 v[110:111], v[110:111], v[154:155], 0 op_sel_hi:[1,1,0]
	s_nop 0
	v_pk_fma_f32 v[110:111], v[112:113], v[156:157], v[110:111]
	v_cvt_pk_f32_fp8_e32 v[112:113], v107
	v_cvt_pk_f32_fp8_sdwa v[106:107], v107 src0_sel:WORD_1
	v_pk_fma_f32 v[110:111], v[112:113], v[158:159], v[110:111]
	s_nop 0
	v_pk_fma_f32 v[106:107], v[106:107], v[162:163], v[110:111]
	v_cvt_pk_f32_fp8_e32 v[110:111], v108
	v_pk_fma_f32 v[106:107], v[110:111], v[164:165], v[106:107]
	v_cvt_pk_f32_fp8_sdwa v[110:111], v108 src0_sel:WORD_1
	v_pk_fma_f32 v[106:107], v[110:111], v[166:167], v[106:107]
	v_cvt_pk_f32_fp8_e32 v[110:111], v109
	v_cvt_pk_f32_fp8_sdwa v[108:109], v109 src0_sel:WORD_1
	v_pk_fma_f32 v[106:107], v[110:111], v[168:169], v[106:107]
	s_nop 0
	v_pk_fma_f32 v[106:107], v[108:109], v[170:171], v[106:107]
	s_waitcnt vmcnt(24)
	v_cvt_pk_f32_fp8_sdwa v[108:109], v102 src0_sel:WORD_1
	v_add_f32_e32 v110, v106, v107
	v_cvt_pk_f32_fp8_e32 v[106:107], v102
	v_pk_fma_f32 v[106:107], v[106:107], v[154:155], 0 op_sel_hi:[1,1,0]
	s_nop 0
	v_pk_fma_f32 v[106:107], v[108:109], v[156:157], v[106:107]
	v_cvt_pk_f32_fp8_e32 v[108:109], v103
	v_cvt_pk_f32_fp8_sdwa v[102:103], v103 src0_sel:WORD_1
	v_pk_fma_f32 v[106:107], v[108:109], v[158:159], v[106:107]
	s_nop 0
	v_pk_fma_f32 v[102:103], v[102:103], v[162:163], v[106:107]
	v_cvt_pk_f32_fp8_e32 v[106:107], v104
	v_pk_fma_f32 v[102:103], v[106:107], v[164:165], v[102:103]
	v_cvt_pk_f32_fp8_sdwa v[106:107], v104 src0_sel:WORD_1
	v_pk_fma_f32 v[102:103], v[106:107], v[166:167], v[102:103]
	v_cvt_pk_f32_fp8_e32 v[106:107], v105
	v_cvt_pk_f32_fp8_sdwa v[104:105], v105 src0_sel:WORD_1
	v_pk_fma_f32 v[102:103], v[106:107], v[168:169], v[102:103]
	s_nop 0
	v_pk_fma_f32 v[102:103], v[104:105], v[170:171], v[102:103]
	s_waitcnt vmcnt(23)
	v_cvt_pk_f32_fp8_sdwa v[104:105], v98 src0_sel:WORD_1
	v_add_f32_e32 v106, v102, v103
	v_cvt_pk_f32_fp8_e32 v[102:103], v98
	v_pk_fma_f32 v[102:103], v[102:103], v[154:155], 0 op_sel_hi:[1,1,0]
	s_nop 0
	v_pk_fma_f32 v[102:103], v[104:105], v[156:157], v[102:103]
	v_cvt_pk_f32_fp8_e32 v[104:105], v99
	v_cvt_pk_f32_fp8_sdwa v[98:99], v99 src0_sel:WORD_1
	v_pk_fma_f32 v[102:103], v[104:105], v[158:159], v[102:103]
	s_nop 0
	v_pk_fma_f32 v[98:99], v[98:99], v[162:163], v[102:103]
	v_cvt_pk_f32_fp8_e32 v[102:103], v100
	v_pk_fma_f32 v[98:99], v[102:103], v[164:165], v[98:99]
	v_cvt_pk_f32_fp8_sdwa v[102:103], v100 src0_sel:WORD_1
	v_pk_fma_f32 v[98:99], v[102:103], v[166:167], v[98:99]
	v_cvt_pk_f32_fp8_e32 v[102:103], v101
	v_cvt_pk_f32_fp8_sdwa v[100:101], v101 src0_sel:WORD_1
	v_pk_fma_f32 v[98:99], v[102:103], v[168:169], v[98:99]
	s_nop 0
	v_pk_fma_f32 v[98:99], v[100:101], v[170:171], v[98:99]
	s_waitcnt vmcnt(22)
	v_cvt_pk_f32_fp8_sdwa v[100:101], v94 src0_sel:WORD_1
	v_add_f32_e32 v102, v98, v99
	v_cvt_pk_f32_fp8_e32 v[98:99], v94
	v_pk_fma_f32 v[98:99], v[98:99], v[154:155], 0 op_sel_hi:[1,1,0]
	s_nop 0
	v_pk_fma_f32 v[98:99], v[100:101], v[156:157], v[98:99]
	v_cvt_pk_f32_fp8_e32 v[100:101], v95
	v_cvt_pk_f32_fp8_sdwa v[94:95], v95 src0_sel:WORD_1
	v_pk_fma_f32 v[98:99], v[100:101], v[158:159], v[98:99]
	s_nop 0
	v_pk_fma_f32 v[94:95], v[94:95], v[162:163], v[98:99]
	v_cvt_pk_f32_fp8_e32 v[98:99], v96
	v_pk_fma_f32 v[94:95], v[98:99], v[164:165], v[94:95]
	v_cvt_pk_f32_fp8_sdwa v[98:99], v96 src0_sel:WORD_1
	v_pk_fma_f32 v[94:95], v[98:99], v[166:167], v[94:95]
	v_cvt_pk_f32_fp8_e32 v[98:99], v97
	v_cvt_pk_f32_fp8_sdwa v[96:97], v97 src0_sel:WORD_1
	v_pk_fma_f32 v[94:95], v[98:99], v[168:169], v[94:95]
	s_nop 0
	v_pk_fma_f32 v[94:95], v[96:97], v[170:171], v[94:95]
	v_cvt_pk_f32_fp8_sdwa v[96:97], v90 src0_sel:WORD_1
	v_add_f32_e32 v98, v94, v95
	v_cvt_pk_f32_fp8_e32 v[94:95], v90
	v_pk_fma_f32 v[94:95], v[94:95], v[154:155], 0 op_sel_hi:[1,1,0]
	s_nop 0
	v_pk_fma_f32 v[94:95], v[96:97], v[156:157], v[94:95]
	v_cvt_pk_f32_fp8_e32 v[96:97], v91
	v_cvt_pk_f32_fp8_sdwa v[90:91], v91 src0_sel:WORD_1
	v_pk_fma_f32 v[94:95], v[96:97], v[158:159], v[94:95]
	s_nop 0
	v_pk_fma_f32 v[90:91], v[90:91], v[162:163], v[94:95]
	v_cvt_pk_f32_fp8_e32 v[94:95], v92
	v_pk_fma_f32 v[90:91], v[94:95], v[164:165], v[90:91]
	v_cvt_pk_f32_fp8_sdwa v[94:95], v92 src0_sel:WORD_1
	v_pk_fma_f32 v[90:91], v[94:95], v[166:167], v[90:91]
	v_cvt_pk_f32_fp8_e32 v[94:95], v93
	v_cvt_pk_f32_fp8_sdwa v[92:93], v93 src0_sel:WORD_1
	v_pk_fma_f32 v[90:91], v[94:95], v[168:169], v[90:91]
	s_nop 0
	v_pk_fma_f32 v[90:91], v[92:93], v[170:171], v[90:91]
	s_waitcnt vmcnt(21)
	v_cvt_pk_f32_fp8_sdwa v[92:93], v86 src0_sel:WORD_1
	v_add_f32_e32 v94, v90, v91
	v_cvt_pk_f32_fp8_e32 v[90:91], v86
	v_pk_fma_f32 v[90:91], v[90:91], v[154:155], 0 op_sel_hi:[1,1,0]
	s_nop 0
	v_pk_fma_f32 v[90:91], v[92:93], v[156:157], v[90:91]
	v_cvt_pk_f32_fp8_e32 v[92:93], v87
	v_cvt_pk_f32_fp8_sdwa v[86:87], v87 src0_sel:WORD_1
	v_pk_fma_f32 v[90:91], v[92:93], v[158:159], v[90:91]
	s_nop 0
	v_pk_fma_f32 v[86:87], v[86:87], v[162:163], v[90:91]
	v_cvt_pk_f32_fp8_e32 v[90:91], v88
	v_pk_fma_f32 v[86:87], v[90:91], v[164:165], v[86:87]
	v_cvt_pk_f32_fp8_sdwa v[90:91], v88 src0_sel:WORD_1
	v_pk_fma_f32 v[86:87], v[90:91], v[166:167], v[86:87]
	v_cvt_pk_f32_fp8_e32 v[90:91], v89
	v_cvt_pk_f32_fp8_sdwa v[88:89], v89 src0_sel:WORD_1
	v_pk_fma_f32 v[86:87], v[90:91], v[168:169], v[86:87]
	s_nop 0
	v_pk_fma_f32 v[86:87], v[88:89], v[170:171], v[86:87]
	s_waitcnt vmcnt(20)
	v_cvt_pk_f32_fp8_sdwa v[88:89], v82 src0_sel:WORD_1
	v_add_f32_e32 v90, v86, v87
	v_cvt_pk_f32_fp8_e32 v[86:87], v82
	v_pk_fma_f32 v[86:87], v[86:87], v[154:155], 0 op_sel_hi:[1,1,0]
	s_nop 0
	v_pk_fma_f32 v[86:87], v[88:89], v[156:157], v[86:87]
	v_cvt_pk_f32_fp8_e32 v[88:89], v83
	v_cvt_pk_f32_fp8_sdwa v[82:83], v83 src0_sel:WORD_1
	v_pk_fma_f32 v[86:87], v[88:89], v[158:159], v[86:87]
	s_nop 0
	v_pk_fma_f32 v[82:83], v[82:83], v[162:163], v[86:87]
	v_cvt_pk_f32_fp8_e32 v[86:87], v84
	v_pk_fma_f32 v[82:83], v[86:87], v[164:165], v[82:83]
	v_cvt_pk_f32_fp8_sdwa v[86:87], v84 src0_sel:WORD_1
	v_pk_fma_f32 v[82:83], v[86:87], v[166:167], v[82:83]
	v_cvt_pk_f32_fp8_e32 v[86:87], v85
	v_cvt_pk_f32_fp8_sdwa v[84:85], v85 src0_sel:WORD_1
	v_pk_fma_f32 v[82:83], v[86:87], v[168:169], v[82:83]
	s_nop 0
	v_pk_fma_f32 v[82:83], v[84:85], v[170:171], v[82:83]
	s_waitcnt vmcnt(19)
	v_cvt_pk_f32_fp8_sdwa v[84:85], v78 src0_sel:WORD_1
	v_add_f32_e32 v86, v82, v83
	v_cvt_pk_f32_fp8_e32 v[82:83], v78
	v_pk_fma_f32 v[82:83], v[82:83], v[154:155], 0 op_sel_hi:[1,1,0]
	s_nop 0
	v_pk_fma_f32 v[82:83], v[84:85], v[156:157], v[82:83]
	v_cvt_pk_f32_fp8_e32 v[84:85], v79
	v_cvt_pk_f32_fp8_sdwa v[78:79], v79 src0_sel:WORD_1
	v_pk_fma_f32 v[82:83], v[84:85], v[158:159], v[82:83]
	s_nop 0
	v_pk_fma_f32 v[78:79], v[78:79], v[162:163], v[82:83]
	v_cvt_pk_f32_fp8_e32 v[82:83], v80
	v_pk_fma_f32 v[78:79], v[82:83], v[164:165], v[78:79]
	v_cvt_pk_f32_fp8_sdwa v[82:83], v80 src0_sel:WORD_1
	v_pk_fma_f32 v[78:79], v[82:83], v[166:167], v[78:79]
	v_cvt_pk_f32_fp8_e32 v[82:83], v81
	v_cvt_pk_f32_fp8_sdwa v[80:81], v81 src0_sel:WORD_1
	v_pk_fma_f32 v[78:79], v[82:83], v[168:169], v[78:79]
	s_nop 0
	v_pk_fma_f32 v[78:79], v[80:81], v[170:171], v[78:79]
	s_waitcnt vmcnt(18)
	v_cvt_pk_f32_fp8_sdwa v[80:81], v74 src0_sel:WORD_1
	v_add_f32_e32 v82, v78, v79
	v_cvt_pk_f32_fp8_e32 v[78:79], v74
	v_pk_fma_f32 v[78:79], v[78:79], v[154:155], 0 op_sel_hi:[1,1,0]
	s_nop 0
	v_pk_fma_f32 v[78:79], v[80:81], v[156:157], v[78:79]
	v_cvt_pk_f32_fp8_e32 v[80:81], v75
	v_cvt_pk_f32_fp8_sdwa v[74:75], v75 src0_sel:WORD_1
	v_pk_fma_f32 v[78:79], v[80:81], v[158:159], v[78:79]
	s_nop 0
	v_pk_fma_f32 v[74:75], v[74:75], v[162:163], v[78:79]
	v_cvt_pk_f32_fp8_e32 v[78:79], v76
	v_pk_fma_f32 v[74:75], v[78:79], v[164:165], v[74:75]
	v_cvt_pk_f32_fp8_sdwa v[78:79], v76 src0_sel:WORD_1
	v_pk_fma_f32 v[74:75], v[78:79], v[166:167], v[74:75]
	v_cvt_pk_f32_fp8_e32 v[78:79], v77
	v_cvt_pk_f32_fp8_sdwa v[76:77], v77 src0_sel:WORD_1
	v_pk_fma_f32 v[74:75], v[78:79], v[168:169], v[74:75]
	s_nop 0
	v_pk_fma_f32 v[74:75], v[76:77], v[170:171], v[74:75]
	s_waitcnt vmcnt(17)
	v_cvt_pk_f32_fp8_sdwa v[76:77], v70 src0_sel:WORD_1
	v_add_f32_e32 v78, v74, v75
	v_cvt_pk_f32_fp8_e32 v[74:75], v70
	v_pk_fma_f32 v[74:75], v[74:75], v[154:155], 0 op_sel_hi:[1,1,0]
	s_nop 0
	v_pk_fma_f32 v[74:75], v[76:77], v[156:157], v[74:75]
	v_cvt_pk_f32_fp8_e32 v[76:77], v71
	v_cvt_pk_f32_fp8_sdwa v[70:71], v71 src0_sel:WORD_1
	v_pk_fma_f32 v[74:75], v[76:77], v[158:159], v[74:75]
	s_nop 0
	v_pk_fma_f32 v[70:71], v[70:71], v[162:163], v[74:75]
	v_cvt_pk_f32_fp8_e32 v[74:75], v72
	s_waitcnt vmcnt(15)
	v_cvt_pk_f32_fp8_e32 v[76:77], v65
	v_pk_fma_f32 v[70:71], v[74:75], v[164:165], v[70:71]
	v_cvt_pk_f32_fp8_sdwa v[74:75], v72 src0_sel:WORD_1
	v_pk_fma_f32 v[70:71], v[74:75], v[166:167], v[70:71]
	v_cvt_pk_f32_fp8_e32 v[74:75], v73
	v_cvt_pk_f32_fp8_sdwa v[72:73], v73 src0_sel:WORD_1
	v_pk_fma_f32 v[70:71], v[74:75], v[168:169], v[70:71]
	s_nop 0
	v_pk_fma_f32 v[70:71], v[72:73], v[170:171], v[70:71]
	v_cvt_pk_f32_fp8_sdwa v[72:73], v66 src0_sel:WORD_1
	v_add_f32_e32 v74, v70, v71
	v_cvt_pk_f32_fp8_e32 v[70:71], v66
	v_pk_fma_f32 v[70:71], v[70:71], v[154:155], 0 op_sel_hi:[1,1,0]
	s_nop 0
	v_pk_fma_f32 v[70:71], v[72:73], v[156:157], v[70:71]
	v_cvt_pk_f32_fp8_e32 v[72:73], v67
	v_cvt_pk_f32_fp8_sdwa v[66:67], v67 src0_sel:WORD_1
	v_pk_fma_f32 v[70:71], v[72:73], v[158:159], v[70:71]
	s_nop 0
	v_pk_fma_f32 v[66:67], v[66:67], v[162:163], v[70:71]
	v_cvt_pk_f32_fp8_e32 v[70:71], v68
	v_pk_fma_f32 v[66:67], v[70:71], v[164:165], v[66:67]
	v_cvt_pk_f32_fp8_sdwa v[70:71], v68 src0_sel:WORD_1
	v_pk_fma_f32 v[66:67], v[70:71], v[166:167], v[66:67]
	v_cvt_pk_f32_fp8_e32 v[70:71], v69
	v_cvt_pk_f32_fp8_sdwa v[68:69], v69 src0_sel:WORD_1
	v_pk_fma_f32 v[66:67], v[70:71], v[168:169], v[66:67]
	s_nop 0
	v_pk_fma_f32 v[66:67], v[68:69], v[170:171], v[66:67]
	v_add_f32_e32 v66, v66, v67
	v_cndmask_b32_e64 v127, v0, v98, s[6:7]
	v_cndmask_b32_e64 v0, v98, v0, s[6:7]
	v_cndmask_b32_e64 v128, v126, v94, s[6:7]
	v_cndmask_b32_e64 v126, v94, v126, s[6:7]
	v_cndmask_b32_e64 v129, v122, v90, s[6:7]
	v_cndmask_b32_e64 v122, v90, v122, s[6:7]
	v_cndmask_b32_e64 v123, v118, v86, s[6:7]
	v_cndmask_b32_e64 v118, v86, v118, s[6:7]
	v_cndmask_b32_e64 v124, v114, v82, s[6:7]
	v_cndmask_b32_e64 v114, v82, v114, s[6:7]
	v_cndmask_b32_e64 v125, v110, v78, s[6:7]
	v_cndmask_b32_e64 v110, v78, v110, s[6:7]
	v_cndmask_b32_e64 v119, v106, v74, s[6:7]
	v_cndmask_b32_e64 v106, v74, v106, s[6:7]
	v_cndmask_b32_e64 v120, v102, v66, s[6:7]
	v_cndmask_b32_e64 v102, v66, v102, s[6:7]
	v_add_f32_dpp v0, v127, v0 quad_perm:[1,0,3,2] row_mask:0xf bank_mask:0xf
	v_add_f32_dpp v126, v128, v126 quad_perm:[1,0,3,2] row_mask:0xf bank_mask:0xf
	v_add_f32_dpp v122, v129, v122 quad_perm:[1,0,3,2] row_mask:0xf bank_mask:0xf
	v_add_f32_dpp v118, v123, v118 quad_perm:[1,0,3,2] row_mask:0xf bank_mask:0xf
	v_add_f32_dpp v114, v124, v114 quad_perm:[1,0,3,2] row_mask:0xf bank_mask:0xf
	v_add_f32_dpp v110, v125, v110 quad_perm:[1,0,3,2] row_mask:0xf bank_mask:0xf
	v_add_f32_dpp v106, v119, v106 quad_perm:[1,0,3,2] row_mask:0xf bank_mask:0xf
	v_add_f32_dpp v102, v120, v102 quad_perm:[1,0,3,2] row_mask:0xf bank_mask:0xf
	v_cndmask_b32_e64 v127, v0, v114, s[8:9]
	v_cndmask_b32_e64 v0, v114, v0, s[8:9]
	v_cndmask_b32_e64 v128, v126, v110, s[8:9]
	v_cndmask_b32_e64 v126, v110, v126, s[8:9]
	v_cndmask_b32_e64 v129, v122, v106, s[8:9]
	v_cndmask_b32_e64 v122, v106, v122, s[8:9]
	v_cndmask_b32_e64 v123, v118, v102, s[8:9]
	v_cndmask_b32_e64 v118, v102, v118, s[8:9]
	v_add_f32_dpp v0, v127, v0 quad_perm:[2,3,0,1] row_mask:0xf bank_mask:0xf
	v_add_f32_dpp v126, v128, v126 quad_perm:[2,3,0,1] row_mask:0xf bank_mask:0xf
	v_add_f32_dpp v122, v129, v122 quad_perm:[2,3,0,1] row_mask:0xf bank_mask:0xf
	v_add_f32_dpp v118, v123, v118 quad_perm:[2,3,0,1] row_mask:0xf bank_mask:0xf
	v_cndmask_b32_e64 v127, v0, v122, s[10:11]
	v_cndmask_b32_e64 v0, v122, v0, s[10:11]
	v_cndmask_b32_e64 v128, v126, v118, s[10:11]
	v_cndmask_b32_e64 v126, v118, v126, s[10:11]
	v_mov_b32_dpp v129, v127 row_half_mirror row_mask:0xf bank_mask:0xf
	v_mov_b32_dpp v123, v128 row_half_mirror row_mask:0xf bank_mask:0xf
	s_nop 0
	v_add_f32_dpp v0, v129, v0 quad_perm:[3,2,1,0] row_mask:0xf bank_mask:0xf
	v_add_f32_dpp v126, v123, v126 quad_perm:[3,2,1,0] row_mask:0xf bank_mask:0xf
	v_cndmask_b32_e64 v127, v0, v126, s[12:13]
	v_cndmask_b32_e64 v0, v126, v0, s[12:13]
	s_nop 1
	v_add_f32_dpp v0, v127, v0 row_ror:8 row_mask:0xf bank_mask:0xf
	s_waitcnt vmcnt(14)
	v_cvt_pk_f32_fp8_e32 v[78:79], v58
	v_cvt_pk_f32_fp8_sdwa v[74:75], v64 src0_sel:WORD_1
	ds_bpermute_b32 v66, v214, v0
	s_waitcnt lgkmcnt(0)
	v_add_f32_e32 v0, v0, v66
	ds_bpermute_b32 v66, v215, v0
	s_waitcnt lgkmcnt(0)
	v_add_f32_e32 v0, v0, v66
	v_add_u32_e32 v66, s1, v151
	ds_read2st64_b32 v[66:67], v66 offset1:2
	s_waitcnt lgkmcnt(0)
	v_mul_f32_e32 v0, v66, v0
	v_mul_f32_e32 v66, 0x3d372713, v0
	v_mul_f32_e32 v66, v0, v66
	v_fma_f32 v66, v0, v66, v0
	v_mul_f32_e32 v66, 0xbfcc422a, v66
	v_mul_f32_e32 v66, 0x3fb8aa3b, v66
	v_exp_f32_e32 v66, v66
	s_nop 0
	v_add_f32_e32 v66, 1.0, v66
	v_div_scale_f32 v68, s[42:43], v66, v66, v0
	v_rcp_f32_e32 v69, v68
	s_nop 0
	v_fma_f32 v70, -v68, v69, 1.0
	v_fmac_f32_e32 v69, v70, v69
	v_div_scale_f32 v70, vcc, v0, v66, v0
	v_mul_f32_e32 v71, v70, v69
	v_fma_f32 v72, -v68, v71, v70
	v_fmac_f32_e32 v71, v72, v69
	v_fma_f32 v68, -v68, v71, v70
	v_div_fmas_f32 v68, v68, v69, v71
	v_div_fixup_f32 v0, v68, v66, v0
	v_mul_f32_e32 v0, v67, v0
	v_cvt_pk_f32_fp8_e32 v[66:67], v62
	v_cvt_pk_f32_fp8_sdwa v[68:69], v62 src0_sel:WORD_1
	v_cvt_pk_f32_fp8_e32 v[70:71], v63
	v_cvt_pk_f32_fp8_sdwa v[62:63], v63 src0_sel:WORD_1
	v_cvt_pk_f32_fp8_e32 v[72:73], v64
	v_cvt_pk_f32_fp8_sdwa v[64:65], v65 src0_sel:WORD_1
	v_readlane_b32 s0, v0, 0
	s_nop 1
	v_pk_fma_f32 v[66:67], v[66:67], s[0:1], v[184:185] op_sel_hi:[1,0,1]
	v_pk_fma_f32 v[68:69], v[68:69], s[0:1], v[186:187] op_sel_hi:[1,0,1]
	v_pk_fma_f32 v[70:71], v[70:71], s[0:1], v[182:183] op_sel_hi:[1,0,1]
	v_pk_fma_f32 v[62:63], v[62:63], s[0:1], v[180:181] op_sel_hi:[1,0,1]
	v_pk_fma_f32 v[72:73], v[72:73], s[0:1], v[178:179] op_sel_hi:[1,0,1]
	v_pk_fma_f32 v[74:75], v[74:75], s[0:1], v[176:177] op_sel_hi:[1,0,1]
	v_pk_fma_f32 v[76:77], v[76:77], s[0:1], v[174:175] op_sel_hi:[1,0,1]
	v_pk_fma_f32 v[64:65], v[64:65], s[0:1], v[172:173] op_sel_hi:[1,0,1]
	v_readlane_b32 s0, v0, 8
	s_nop 1
	v_pk_fma_f32 v[66:67], v[78:79], s[0:1], v[66:67] op_sel_hi:[1,0,1]
	v_cvt_pk_f32_fp8_sdwa v[78:79], v58 src0_sel:WORD_1
	v_pk_fma_f32 v[68:69], v[78:79], s[0:1], v[68:69] op_sel_hi:[1,0,1]
	v_cvt_pk_f32_fp8_e32 v[78:79], v59
	v_cvt_pk_f32_fp8_sdwa v[58:59], v59 src0_sel:WORD_1
	v_pk_fma_f32 v[70:71], v[78:79], s[0:1], v[70:71] op_sel_hi:[1,0,1]
	v_pk_fma_f32 v[58:59], v[58:59], s[0:1], v[62:63] op_sel_hi:[1,0,1]
	v_cvt_pk_f32_fp8_e32 v[62:63], v60
	v_pk_fma_f32 v[62:63], v[62:63], s[0:1], v[72:73] op_sel_hi:[1,0,1]
	v_cvt_pk_f32_fp8_sdwa v[72:73], v60 src0_sel:WORD_1
	v_pk_fma_f32 v[72:73], v[72:73], s[0:1], v[74:75] op_sel_hi:[1,0,1]
	v_cvt_pk_f32_fp8_e32 v[74:75], v61
	v_cvt_pk_f32_fp8_sdwa v[60:61], v61 src0_sel:WORD_1
	v_pk_fma_f32 v[74:75], v[74:75], s[0:1], v[76:77] op_sel_hi:[1,0,1]
	v_pk_fma_f32 v[60:61], v[60:61], s[0:1], v[64:65] op_sel_hi:[1,0,1]
	s_waitcnt vmcnt(13)
	v_cvt_pk_f32_fp8_e32 v[64:65], v54
	v_readlane_b32 s0, v0, 4
	s_nop 1
	v_pk_fma_f32 v[64:65], v[64:65], s[0:1], v[66:67] op_sel_hi:[1,0,1]
	v_cvt_pk_f32_fp8_sdwa v[66:67], v54 src0_sel:WORD_1
	v_pk_fma_f32 v[66:67], v[66:67], s[0:1], v[68:69] op_sel_hi:[1,0,1]
	v_cvt_pk_f32_fp8_e32 v[68:69], v55
	v_cvt_pk_f32_fp8_sdwa v[54:55], v55 src0_sel:WORD_1
	v_pk_fma_f32 v[68:69], v[68:69], s[0:1], v[70:71] op_sel_hi:[1,0,1]
	v_pk_fma_f32 v[54:55], v[54:55], s[0:1], v[58:59] op_sel_hi:[1,0,1]
	v_cvt_pk_f32_fp8_e32 v[58:59], v56
	v_cvt_pk_f32_fp8_e32 v[70:71], v57
	v_pk_fma_f32 v[58:59], v[58:59], s[0:1], v[62:63] op_sel_hi:[1,0,1]
	v_cvt_pk_f32_fp8_sdwa v[62:63], v56 src0_sel:WORD_1
	v_cvt_pk_f32_fp8_sdwa v[56:57], v57 src0_sel:WORD_1
	v_pk_fma_f32 v[70:71], v[70:71], s[0:1], v[74:75] op_sel_hi:[1,0,1]
	v_pk_fma_f32 v[62:63], v[62:63], s[0:1], v[72:73] op_sel_hi:[1,0,1]
	v_pk_fma_f32 v[56:57], v[56:57], s[0:1], v[60:61] op_sel_hi:[1,0,1]
	s_waitcnt vmcnt(12)
	v_cvt_pk_f32_fp8_e32 v[60:61], v50
	v_readlane_b32 s0, v0, 12
	s_nop 1
	v_pk_fma_f32 v[60:61], v[60:61], s[0:1], v[64:65] op_sel_hi:[1,0,1]
	v_cvt_pk_f32_fp8_sdwa v[64:65], v50 src0_sel:WORD_1
	v_pk_fma_f32 v[64:65], v[64:65], s[0:1], v[66:67] op_sel_hi:[1,0,1]
	v_cvt_pk_f32_fp8_e32 v[66:67], v51
	v_cvt_pk_f32_fp8_sdwa v[50:51], v51 src0_sel:WORD_1
	v_pk_fma_f32 v[66:67], v[66:67], s[0:1], v[68:69] op_sel_hi:[1,0,1]
	v_pk_fma_f32 v[50:51], v[50:51], s[0:1], v[54:55] op_sel_hi:[1,0,1]
	v_cvt_pk_f32_fp8_e32 v[54:55], v52
	v_pk_fma_f32 v[54:55], v[54:55], s[0:1], v[58:59] op_sel_hi:[1,0,1]
	v_cvt_pk_f32_fp8_sdwa v[58:59], v52 src0_sel:WORD_1
	v_pk_fma_f32 v[58:59], v[58:59], s[0:1], v[62:63] op_sel_hi:[1,0,1]
	v_cvt_pk_f32_fp8_e32 v[62:63], v53
	v_cvt_pk_f32_fp8_sdwa v[52:53], v53 src0_sel:WORD_1
	v_pk_fma_f32 v[62:63], v[62:63], s[0:1], v[70:71] op_sel_hi:[1,0,1]
	v_pk_fma_f32 v[52:53], v[52:53], s[0:1], v[56:57] op_sel_hi:[1,0,1]
	s_waitcnt vmcnt(11)
	v_cvt_pk_f32_fp8_e32 v[56:57], v46
	v_readlane_b32 s0, v0, 2
	s_nop 1
	v_pk_fma_f32 v[56:57], v[56:57], s[0:1], v[60:61] op_sel_hi:[1,0,1]
	v_cvt_pk_f32_fp8_sdwa v[60:61], v46 src0_sel:WORD_1
	v_pk_fma_f32 v[60:61], v[60:61], s[0:1], v[64:65] op_sel_hi:[1,0,1]
	v_cvt_pk_f32_fp8_e32 v[64:65], v47
	v_cvt_pk_f32_fp8_sdwa v[46:47], v47 src0_sel:WORD_1
	v_pk_fma_f32 v[64:65], v[64:65], s[0:1], v[66:67] op_sel_hi:[1,0,1]
	v_pk_fma_f32 v[46:47], v[46:47], s[0:1], v[50:51] op_sel_hi:[1,0,1]
	v_cvt_pk_f32_fp8_e32 v[50:51], v48
	v_pk_fma_f32 v[50:51], v[50:51], s[0:1], v[54:55] op_sel_hi:[1,0,1]
	v_cvt_pk_f32_fp8_sdwa v[54:55], v48 src0_sel:WORD_1
	v_pk_fma_f32 v[54:55], v[54:55], s[0:1], v[58:59] op_sel_hi:[1,0,1]
	v_cvt_pk_f32_fp8_e32 v[58:59], v49
	v_cvt_pk_f32_fp8_sdwa v[48:49], v49 src0_sel:WORD_1
	v_pk_fma_f32 v[58:59], v[58:59], s[0:1], v[62:63] op_sel_hi:[1,0,1]
	v_pk_fma_f32 v[48:49], v[48:49], s[0:1], v[52:53] op_sel_hi:[1,0,1]
	s_waitcnt vmcnt(10)
	v_cvt_pk_f32_fp8_e32 v[52:53], v42
	v_readlane_b32 s0, v0, 10
	s_nop 1
	v_pk_fma_f32 v[52:53], v[52:53], s[0:1], v[56:57] op_sel_hi:[1,0,1]
	v_cvt_pk_f32_fp8_sdwa v[56:57], v42 src0_sel:WORD_1
	v_pk_fma_f32 v[56:57], v[56:57], s[0:1], v[60:61] op_sel_hi:[1,0,1]
	v_cvt_pk_f32_fp8_e32 v[60:61], v43
	v_cvt_pk_f32_fp8_sdwa v[42:43], v43 src0_sel:WORD_1
	v_pk_fma_f32 v[60:61], v[60:61], s[0:1], v[64:65] op_sel_hi:[1,0,1]
	v_pk_fma_f32 v[42:43], v[42:43], s[0:1], v[46:47] op_sel_hi:[1,0,1]
	v_cvt_pk_f32_fp8_e32 v[46:47], v44
	v_pk_fma_f32 v[46:47], v[46:47], s[0:1], v[50:51] op_sel_hi:[1,0,1]
	v_cvt_pk_f32_fp8_sdwa v[50:51], v44 src0_sel:WORD_1
	v_pk_fma_f32 v[50:51], v[50:51], s[0:1], v[54:55] op_sel_hi:[1,0,1]
	v_cvt_pk_f32_fp8_e32 v[54:55], v45
	v_cvt_pk_f32_fp8_sdwa v[44:45], v45 src0_sel:WORD_1
	v_pk_fma_f32 v[54:55], v[54:55], s[0:1], v[58:59] op_sel_hi:[1,0,1]
	v_pk_fma_f32 v[44:45], v[44:45], s[0:1], v[48:49] op_sel_hi:[1,0,1]
	s_waitcnt vmcnt(9)
	v_cvt_pk_f32_fp8_e32 v[48:49], v38
	v_readlane_b32 s0, v0, 6
	s_nop 1
	v_pk_fma_f32 v[48:49], v[48:49], s[0:1], v[52:53] op_sel_hi:[1,0,1]
	v_cvt_pk_f32_fp8_sdwa v[52:53], v38 src0_sel:WORD_1
	v_pk_fma_f32 v[52:53], v[52:53], s[0:1], v[56:57] op_sel_hi:[1,0,1]
	v_cvt_pk_f32_fp8_e32 v[56:57], v39
	v_cvt_pk_f32_fp8_sdwa v[38:39], v39 src0_sel:WORD_1
	v_pk_fma_f32 v[56:57], v[56:57], s[0:1], v[60:61] op_sel_hi:[1,0,1]
	v_pk_fma_f32 v[38:39], v[38:39], s[0:1], v[42:43] op_sel_hi:[1,0,1]
	v_cvt_pk_f32_fp8_e32 v[42:43], v40
	v_pk_fma_f32 v[42:43], v[42:43], s[0:1], v[46:47] op_sel_hi:[1,0,1]
	v_cvt_pk_f32_fp8_sdwa v[46:47], v40 src0_sel:WORD_1
	v_pk_fma_f32 v[46:47], v[46:47], s[0:1], v[50:51] op_sel_hi:[1,0,1]
	v_cvt_pk_f32_fp8_e32 v[50:51], v41
	v_cvt_pk_f32_fp8_sdwa v[40:41], v41 src0_sel:WORD_1
	v_pk_fma_f32 v[50:51], v[50:51], s[0:1], v[54:55] op_sel_hi:[1,0,1]
	v_pk_fma_f32 v[40:41], v[40:41], s[0:1], v[44:45] op_sel_hi:[1,0,1]
	s_waitcnt vmcnt(8)
	v_cvt_pk_f32_fp8_e32 v[44:45], v34
	v_readlane_b32 s0, v0, 14
	s_nop 1
	v_pk_fma_f32 v[44:45], v[44:45], s[0:1], v[48:49] op_sel_hi:[1,0,1]
	v_cvt_pk_f32_fp8_sdwa v[48:49], v34 src0_sel:WORD_1
	v_pk_fma_f32 v[48:49], v[48:49], s[0:1], v[52:53] op_sel_hi:[1,0,1]
	v_cvt_pk_f32_fp8_e32 v[52:53], v35
	v_cvt_pk_f32_fp8_sdwa v[34:35], v35 src0_sel:WORD_1
	v_pk_fma_f32 v[52:53], v[52:53], s[0:1], v[56:57] op_sel_hi:[1,0,1]
	v_pk_fma_f32 v[34:35], v[34:35], s[0:1], v[38:39] op_sel_hi:[1,0,1]
	v_cvt_pk_f32_fp8_e32 v[38:39], v36
	v_pk_fma_f32 v[38:39], v[38:39], s[0:1], v[42:43] op_sel_hi:[1,0,1]
	v_cvt_pk_f32_fp8_sdwa v[42:43], v36 src0_sel:WORD_1
	v_pk_fma_f32 v[42:43], v[42:43], s[0:1], v[46:47] op_sel_hi:[1,0,1]
	v_cvt_pk_f32_fp8_e32 v[46:47], v37
	v_cvt_pk_f32_fp8_sdwa v[36:37], v37 src0_sel:WORD_1
	v_pk_fma_f32 v[46:47], v[46:47], s[0:1], v[50:51] op_sel_hi:[1,0,1]
	v_pk_fma_f32 v[36:37], v[36:37], s[0:1], v[40:41] op_sel_hi:[1,0,1]
	s_waitcnt vmcnt(7)
	v_cvt_pk_f32_fp8_e32 v[40:41], v30
	v_readlane_b32 s0, v0, 1
	s_nop 1
	v_pk_fma_f32 v[40:41], v[40:41], s[0:1], v[44:45] op_sel_hi:[1,0,1]
	v_cvt_pk_f32_fp8_sdwa v[44:45], v30 src0_sel:WORD_1
	v_pk_fma_f32 v[44:45], v[44:45], s[0:1], v[48:49] op_sel_hi:[1,0,1]
	v_cvt_pk_f32_fp8_e32 v[48:49], v31
	v_cvt_pk_f32_fp8_sdwa v[30:31], v31 src0_sel:WORD_1
	v_pk_fma_f32 v[48:49], v[48:49], s[0:1], v[52:53] op_sel_hi:[1,0,1]
	v_pk_fma_f32 v[30:31], v[30:31], s[0:1], v[34:35] op_sel_hi:[1,0,1]
	v_cvt_pk_f32_fp8_e32 v[34:35], v32
	v_pk_fma_f32 v[34:35], v[34:35], s[0:1], v[38:39] op_sel_hi:[1,0,1]
	v_cvt_pk_f32_fp8_sdwa v[38:39], v32 src0_sel:WORD_1
	v_pk_fma_f32 v[38:39], v[38:39], s[0:1], v[42:43] op_sel_hi:[1,0,1]
	v_cvt_pk_f32_fp8_e32 v[42:43], v33
	v_cvt_pk_f32_fp8_sdwa v[32:33], v33 src0_sel:WORD_1
	v_pk_fma_f32 v[42:43], v[42:43], s[0:1], v[46:47] op_sel_hi:[1,0,1]
	v_pk_fma_f32 v[32:33], v[32:33], s[0:1], v[36:37] op_sel_hi:[1,0,1]
	s_waitcnt vmcnt(6)
	v_cvt_pk_f32_fp8_e32 v[36:37], v26
	v_readlane_b32 s0, v0, 9
	s_nop 1
	v_pk_fma_f32 v[36:37], v[36:37], s[0:1], v[40:41] op_sel_hi:[1,0,1]
	v_cvt_pk_f32_fp8_sdwa v[40:41], v26 src0_sel:WORD_1
	v_pk_fma_f32 v[40:41], v[40:41], s[0:1], v[44:45] op_sel_hi:[1,0,1]
	v_cvt_pk_f32_fp8_e32 v[44:45], v27
	v_cvt_pk_f32_fp8_sdwa v[26:27], v27 src0_sel:WORD_1
	v_pk_fma_f32 v[44:45], v[44:45], s[0:1], v[48:49] op_sel_hi:[1,0,1]
	v_pk_fma_f32 v[26:27], v[26:27], s[0:1], v[30:31] op_sel_hi:[1,0,1]
	v_cvt_pk_f32_fp8_e32 v[30:31], v28
	v_pk_fma_f32 v[30:31], v[30:31], s[0:1], v[34:35] op_sel_hi:[1,0,1]
	v_cvt_pk_f32_fp8_sdwa v[34:35], v28 src0_sel:WORD_1
	v_pk_fma_f32 v[34:35], v[34:35], s[0:1], v[38:39] op_sel_hi:[1,0,1]
	v_cvt_pk_f32_fp8_e32 v[38:39], v29
	v_cvt_pk_f32_fp8_sdwa v[28:29], v29 src0_sel:WORD_1
	v_pk_fma_f32 v[38:39], v[38:39], s[0:1], v[42:43] op_sel_hi:[1,0,1]
	v_pk_fma_f32 v[28:29], v[28:29], s[0:1], v[32:33] op_sel_hi:[1,0,1]
	s_waitcnt vmcnt(5)
	v_cvt_pk_f32_fp8_e32 v[32:33], v22
	v_readlane_b32 s0, v0, 5
	s_nop 1
	v_pk_fma_f32 v[32:33], v[32:33], s[0:1], v[36:37] op_sel_hi:[1,0,1]
	v_cvt_pk_f32_fp8_sdwa v[36:37], v22 src0_sel:WORD_1
	v_pk_fma_f32 v[36:37], v[36:37], s[0:1], v[40:41] op_sel_hi:[1,0,1]
	v_cvt_pk_f32_fp8_e32 v[40:41], v23
	v_cvt_pk_f32_fp8_sdwa v[22:23], v23 src0_sel:WORD_1
	v_pk_fma_f32 v[40:41], v[40:41], s[0:1], v[44:45] op_sel_hi:[1,0,1]
	v_pk_fma_f32 v[22:23], v[22:23], s[0:1], v[26:27] op_sel_hi:[1,0,1]
	v_cvt_pk_f32_fp8_e32 v[26:27], v24
	v_pk_fma_f32 v[26:27], v[26:27], s[0:1], v[30:31] op_sel_hi:[1,0,1]
	v_cvt_pk_f32_fp8_sdwa v[30:31], v24 src0_sel:WORD_1
	v_pk_fma_f32 v[30:31], v[30:31], s[0:1], v[34:35] op_sel_hi:[1,0,1]
	v_cvt_pk_f32_fp8_e32 v[34:35], v25
	v_cvt_pk_f32_fp8_sdwa v[24:25], v25 src0_sel:WORD_1
	v_pk_fma_f32 v[34:35], v[34:35], s[0:1], v[38:39] op_sel_hi:[1,0,1]
	v_pk_fma_f32 v[24:25], v[24:25], s[0:1], v[28:29] op_sel_hi:[1,0,1]
	s_waitcnt vmcnt(4)
	v_cvt_pk_f32_fp8_e32 v[28:29], v18
	v_readlane_b32 s0, v0, 13
	s_nop 1
	v_pk_fma_f32 v[28:29], v[28:29], s[0:1], v[32:33] op_sel_hi:[1,0,1]
	v_cvt_pk_f32_fp8_sdwa v[32:33], v18 src0_sel:WORD_1
	v_pk_fma_f32 v[32:33], v[32:33], s[0:1], v[36:37] op_sel_hi:[1,0,1]
	v_cvt_pk_f32_fp8_e32 v[36:37], v19
	v_cvt_pk_f32_fp8_sdwa v[18:19], v19 src0_sel:WORD_1
	v_pk_fma_f32 v[36:37], v[36:37], s[0:1], v[40:41] op_sel_hi:[1,0,1]
	v_pk_fma_f32 v[18:19], v[18:19], s[0:1], v[22:23] op_sel_hi:[1,0,1]
	v_cvt_pk_f32_fp8_e32 v[22:23], v20
	v_pk_fma_f32 v[22:23], v[22:23], s[0:1], v[26:27] op_sel_hi:[1,0,1]
	v_cvt_pk_f32_fp8_sdwa v[26:27], v20 src0_sel:WORD_1
	v_pk_fma_f32 v[26:27], v[26:27], s[0:1], v[30:31] op_sel_hi:[1,0,1]
	v_cvt_pk_f32_fp8_e32 v[30:31], v21
	v_cvt_pk_f32_fp8_sdwa v[20:21], v21 src0_sel:WORD_1
	v_pk_fma_f32 v[30:31], v[30:31], s[0:1], v[34:35] op_sel_hi:[1,0,1]
	v_pk_fma_f32 v[20:21], v[20:21], s[0:1], v[24:25] op_sel_hi:[1,0,1]
	s_waitcnt vmcnt(3)
	v_cvt_pk_f32_fp8_e32 v[24:25], v14
	v_readlane_b32 s0, v0, 3
	s_nop 1
	v_pk_fma_f32 v[24:25], v[24:25], s[0:1], v[28:29] op_sel_hi:[1,0,1]
	v_cvt_pk_f32_fp8_sdwa v[28:29], v14 src0_sel:WORD_1
	v_pk_fma_f32 v[28:29], v[28:29], s[0:1], v[32:33] op_sel_hi:[1,0,1]
	v_cvt_pk_f32_fp8_e32 v[32:33], v15
	v_cvt_pk_f32_fp8_sdwa v[14:15], v15 src0_sel:WORD_1
	v_pk_fma_f32 v[32:33], v[32:33], s[0:1], v[36:37] op_sel_hi:[1,0,1]
	v_pk_fma_f32 v[14:15], v[14:15], s[0:1], v[18:19] op_sel_hi:[1,0,1]
	v_cvt_pk_f32_fp8_e32 v[18:19], v16
	v_pk_fma_f32 v[18:19], v[18:19], s[0:1], v[22:23] op_sel_hi:[1,0,1]
	v_cvt_pk_f32_fp8_sdwa v[22:23], v16 src0_sel:WORD_1
	v_pk_fma_f32 v[22:23], v[22:23], s[0:1], v[26:27] op_sel_hi:[1,0,1]
	v_cvt_pk_f32_fp8_e32 v[26:27], v17
	v_cvt_pk_f32_fp8_sdwa v[16:17], v17 src0_sel:WORD_1
	v_pk_fma_f32 v[26:27], v[26:27], s[0:1], v[30:31] op_sel_hi:[1,0,1]
	v_pk_fma_f32 v[16:17], v[16:17], s[0:1], v[20:21] op_sel_hi:[1,0,1]
	s_waitcnt vmcnt(2)
	v_cvt_pk_f32_fp8_e32 v[20:21], v10
	v_readlane_b32 s0, v0, 11
	s_nop 1
	v_pk_fma_f32 v[20:21], v[20:21], s[0:1], v[24:25] op_sel_hi:[1,0,1]
	v_cvt_pk_f32_fp8_sdwa v[24:25], v10 src0_sel:WORD_1
	v_pk_fma_f32 v[24:25], v[24:25], s[0:1], v[28:29] op_sel_hi:[1,0,1]
	v_cvt_pk_f32_fp8_e32 v[28:29], v11
	v_cvt_pk_f32_fp8_sdwa v[10:11], v11 src0_sel:WORD_1
	v_pk_fma_f32 v[28:29], v[28:29], s[0:1], v[32:33] op_sel_hi:[1,0,1]
	v_pk_fma_f32 v[10:11], v[10:11], s[0:1], v[14:15] op_sel_hi:[1,0,1]
	v_cvt_pk_f32_fp8_e32 v[14:15], v12
	v_pk_fma_f32 v[14:15], v[14:15], s[0:1], v[18:19] op_sel_hi:[1,0,1]
	v_cvt_pk_f32_fp8_sdwa v[18:19], v12 src0_sel:WORD_1
	v_pk_fma_f32 v[18:19], v[18:19], s[0:1], v[22:23] op_sel_hi:[1,0,1]
	v_cvt_pk_f32_fp8_e32 v[22:23], v13
	v_cvt_pk_f32_fp8_sdwa v[12:13], v13 src0_sel:WORD_1
	v_pk_fma_f32 v[22:23], v[22:23], s[0:1], v[26:27] op_sel_hi:[1,0,1]
	v_pk_fma_f32 v[12:13], v[12:13], s[0:1], v[16:17] op_sel_hi:[1,0,1]
	s_waitcnt vmcnt(1)
	v_cvt_pk_f32_fp8_e32 v[16:17], v6
	v_readlane_b32 s0, v0, 7
	s_nop 1
	v_pk_fma_f32 v[16:17], v[16:17], s[0:1], v[20:21] op_sel_hi:[1,0,1]
	v_cvt_pk_f32_fp8_sdwa v[20:21], v6 src0_sel:WORD_1
	v_pk_fma_f32 v[20:21], v[20:21], s[0:1], v[24:25] op_sel_hi:[1,0,1]
	v_cvt_pk_f32_fp8_e32 v[24:25], v7
	v_cvt_pk_f32_fp8_sdwa v[6:7], v7 src0_sel:WORD_1
	v_pk_fma_f32 v[24:25], v[24:25], s[0:1], v[28:29] op_sel_hi:[1,0,1]
	v_pk_fma_f32 v[6:7], v[6:7], s[0:1], v[10:11] op_sel_hi:[1,0,1]
	v_cvt_pk_f32_fp8_e32 v[10:11], v8
	v_pk_fma_f32 v[10:11], v[10:11], s[0:1], v[14:15] op_sel_hi:[1,0,1]
	v_cvt_pk_f32_fp8_sdwa v[14:15], v8 src0_sel:WORD_1
	v_pk_fma_f32 v[14:15], v[14:15], s[0:1], v[18:19] op_sel_hi:[1,0,1]
	v_cvt_pk_f32_fp8_e32 v[18:19], v9
	v_cvt_pk_f32_fp8_sdwa v[8:9], v9 src0_sel:WORD_1
	v_pk_fma_f32 v[18:19], v[18:19], s[0:1], v[22:23] op_sel_hi:[1,0,1]
	v_pk_fma_f32 v[8:9], v[8:9], s[0:1], v[12:13] op_sel_hi:[1,0,1]
	s_waitcnt vmcnt(0)
	v_cvt_pk_f32_fp8_e32 v[12:13], v2
	v_readlane_b32 s0, v0, 15
	s_nop 1
	v_pk_fma_f32 v[184:185], v[12:13], s[0:1], v[16:17] op_sel_hi:[1,0,1]
	v_cvt_pk_f32_fp8_sdwa v[12:13], v2 src0_sel:WORD_1
	v_pk_fma_f32 v[186:187], v[12:13], s[0:1], v[20:21] op_sel_hi:[1,0,1]
	v_cvt_pk_f32_fp8_e32 v[12:13], v3
	v_cvt_pk_f32_fp8_sdwa v[2:3], v3 src0_sel:WORD_1
	v_pk_fma_f32 v[182:183], v[12:13], s[0:1], v[24:25] op_sel_hi:[1,0,1]
	v_pk_fma_f32 v[180:181], v[2:3], s[0:1], v[6:7] op_sel_hi:[1,0,1]
	v_cvt_pk_f32_fp8_e32 v[2:3], v4
	v_pk_fma_f32 v[178:179], v[2:3], s[0:1], v[10:11] op_sel_hi:[1,0,1]
	v_cvt_pk_f32_fp8_sdwa v[2:3], v4 src0_sel:WORD_1
	v_pk_fma_f32 v[176:177], v[2:3], s[0:1], v[14:15] op_sel_hi:[1,0,1]
	v_cvt_pk_f32_fp8_e32 v[2:3], v5
	v_pk_fma_f32 v[174:175], v[2:3], s[0:1], v[18:19] op_sel_hi:[1,0,1]
	v_cvt_pk_f32_fp8_sdwa v[2:3], v5 src0_sel:WORD_1
	v_pk_fma_f32 v[172:173], v[2:3], s[0:1], v[8:9] op_sel_hi:[1,0,1]
	s_add_i32 s1, s1, 64
	s_cmpk_lg_i32 s1, 0x200
	s_cbranch_scc1 .LBB0_870
	s_setprio 3
	v_add_u32_e32 v0, 0xfffff000, v152
	v_lshrrev_b32_e32 v0, 10, v0
	v_add_u32_e32 v0, 1, v0
	v_cmp_lt_i32_e32 vcc, s57, v152
	v_mov_b64_e32 v[2:3], s[16:17]
	v_lshlrev_b64 v[4:5], 12, v[152:153]
	v_cndmask_b32_e32 v0, 0, v0, vcc
	v_add_u32_e32 v46, s40, v0
	v_mad_u64_u32 v[2:3], s[0:1], v46, s63, v[2:3]
	v_lshlrev_b32_e32 v0, 2, v136
	v_lshl_add_u64 v[2:3], v[2:3], 0, v[0:1]
	s_mov_b64 s[0:1], 0x5000
	v_lshl_add_u64 v[52:53], v[2:3], 0, s[0:1]
	s_movk_i32 s0, 0x5000
	v_lshl_add_u64 v[40:41], v[142:143], 0, v[4:5]
	v_add_co_u32_e32 v2, vcc, s0, v2
	global_load_dwordx4 v[10:13], v[40:41], off
	s_nop 0
	v_addc_co_u32_e32 v3, vcc, 0, v3, vcc
	global_load_dwordx4 v[16:19], v[2:3], off
	s_nop 0
	global_load_dwordx4 v[2:5], v[146:147], off
	global_load_dwordx4 v[6:9], v[148:149], off
	v_lshlrev_b64 v[38:39], 10, v[152:153]
	s_mov_b64 s[0:1], -1
	s_waitcnt vmcnt(2)
	v_pk_mul_f32 v[14:15], v[184:185], v[16:17]
	s_nop 0
	v_pk_fma_f32 v[16:17], v[10:11], s[86:87], v[14:15] op_sel_hi:[1,0,1]
	s_nop 0
	v_add_f32_e32 v10, 0, v16
	v_add_f32_e32 v20, v17, v10
	v_pk_mul_f32 v[10:11], v[186:187], v[18:19]
	s_nop 0
	v_pk_fma_f32 v[14:15], v[12:13], s[86:87], v[10:11] op_sel_hi:[1,0,1]
	s_nop 0
	v_add_f32_e32 v10, v14, v20
	v_add_f32_e32 v30, v15, v10
	global_load_dwordx4 v[22:25], v[40:41], off offset:1024
	global_load_dwordx4 v[26:29], v[52:53], off offset:1024
	global_load_dwordx4 v[10:13], v[146:147], off offset:1024
	global_load_dwordx4 v[18:21], v[148:149], off offset:1024
	s_waitcnt vmcnt(2)
	v_pk_mul_f32 v[26:27], v[182:183], v[26:27]
	s_nop 0
	v_pk_fma_f32 v[44:45], v[22:23], s[86:87], v[26:27] op_sel_hi:[1,0,1]
	s_nop 0
	v_add_f32_e32 v22, v44, v30
	v_add_f32_e32 v26, v45, v22
	v_pk_mul_f32 v[22:23], v[180:181], v[28:29]
	s_nop 0
	v_pk_fma_f32 v[42:43], v[24:25], s[86:87], v[22:23] op_sel_hi:[1,0,1]
	s_nop 0
	v_add_f32_e32 v22, v42, v26
	v_add_f32_e32 v47, v43, v22
	global_load_dwordx4 v[30:33], v[40:41], off offset:2048
	global_load_dwordx4 v[34:37], v[52:53], off offset:2048
	global_load_dwordx4 v[22:25], v[146:147], off offset:2048
	global_load_dwordx4 v[26:29], v[148:149], off offset:2048
	s_waitcnt vmcnt(2)
	v_pk_mul_f32 v[34:35], v[178:179], v[34:35]
	s_nop 0
	v_pk_fma_f32 v[56:57], v[30:31], s[86:87], v[34:35] op_sel_hi:[1,0,1]
	s_nop 0
	v_add_f32_e32 v30, v56, v47
	v_add_f32_e32 v34, v57, v30
	v_pk_mul_f32 v[30:31], v[176:177], v[36:37]
	s_nop 0
	v_pk_fma_f32 v[58:59], v[32:33], s[86:87], v[30:31] op_sel_hi:[1,0,1]
	s_nop 0
	v_add_f32_e32 v30, v58, v34
	v_add_f32_e32 v47, v59, v30
	global_load_dwordx4 v[48:51], v[40:41], off offset:3072
	s_nop 0
	global_load_dwordx4 v[52:55], v[52:53], off offset:3072
	s_nop 0
	global_load_dwordx4 v[30:33], v[146:147], off offset:3072
	global_load_dwordx4 v[34:37], v[148:149], off offset:3072
	s_waitcnt vmcnt(2)
	v_pk_mul_f32 v[52:53], v[174:175], v[52:53]
	s_nop 0
	v_pk_fma_f32 v[48:49], v[48:49], s[86:87], v[52:53] op_sel_hi:[1,0,1]
	v_pk_mul_f32 v[52:53], v[172:173], v[54:55]
	v_add_f32_e32 v47, v48, v47
	v_add_f32_e32 v47, v49, v47
	v_pk_fma_f32 v[50:51], v[50:51], s[86:87], v[52:53] op_sel_hi:[1,0,1]
	s_nop 0
	v_add_f32_e32 v47, v50, v47
	v_add_f32_e32 v47, v51, v47
	ds_bpermute_b32 v52, v215, v47
	s_waitcnt lgkmcnt(0)
	v_add_f32_e32 v47, v47, v52
	ds_bpermute_b32 v52, v214, v47
	s_waitcnt lgkmcnt(0)
	v_add_f32_e32 v47, v47, v52
	s_waitcnt lgkmcnt(0)
	s_nop 1
	v_add_f32_dpp v47, v47, v47 row_ror:8 row_mask:0xf bank_mask:0xf
	s_waitcnt lgkmcnt(0)
	s_nop 1
	v_mov_b32_dpp v52, v47 row_half_mirror row_mask:0xf bank_mask:0xf
	s_nop 1
	v_add_f32_dpp v47, v52, v47 quad_perm:[3,2,1,0] row_mask:0xf bank_mask:0xf
	s_waitcnt lgkmcnt(0)
	s_nop 1
	v_add_f32_dpp v47, v47, v47 quad_perm:[2,3,0,1] row_mask:0xf bank_mask:0xf
	s_waitcnt lgkmcnt(0)
	s_nop 1
	v_add_f32_dpp v47, v47, v47 quad_perm:[1,0,3,2] row_mask:0xf bank_mask:0xf
	v_mul_f32_e32 v52, 0x3a800000, v47
	v_pk_add_f32 v[16:17], v[16:17], v[52:53] op_sel_hi:[1,0] neg_lo:[0,1] neg_hi:[0,1]
	v_pk_add_f32 v[60:61], v[14:15], v[52:53] op_sel_hi:[1,0] neg_lo:[0,1] neg_hi:[0,1]
	v_pk_mul_f32 v[54:55], v[16:17], v[16:17]
	v_pk_mul_f32 v[14:15], v[60:61], v[60:61]
	v_add_f32_e32 v47, v54, v55
	v_pk_add_f32 v[44:45], v[44:45], v[52:53] op_sel_hi:[1,0] neg_lo:[0,1] neg_hi:[0,1]
	v_add_f32_e32 v14, v14, v47
	v_pk_mul_f32 v[62:63], v[44:45], v[44:45]
	v_add_f32_e32 v14, v15, v14
	v_pk_add_f32 v[42:43], v[42:43], v[52:53] op_sel_hi:[1,0] neg_lo:[0,1] neg_hi:[0,1]
	v_add_f32_e32 v14, v62, v14
	v_pk_mul_f32 v[64:65], v[42:43], v[42:43]
	v_add_f32_e32 v14, v63, v14
	v_pk_add_f32 v[56:57], v[56:57], v[52:53] op_sel_hi:[1,0] neg_lo:[0,1] neg_hi:[0,1]
	v_add_f32_e32 v14, v64, v14
	v_pk_mul_f32 v[66:67], v[56:57], v[56:57]
	v_add_f32_e32 v14, v65, v14
	v_pk_add_f32 v[58:59], v[58:59], v[52:53] op_sel_hi:[1,0] neg_lo:[0,1] neg_hi:[0,1]
	v_add_f32_e32 v14, v66, v14
	v_pk_mul_f32 v[68:69], v[58:59], v[58:59]
	v_add_f32_e32 v14, v67, v14
	v_pk_add_f32 v[48:49], v[48:49], v[52:53] op_sel_hi:[1,0] neg_lo:[0,1] neg_hi:[0,1]
	v_add_f32_e32 v14, v68, v14
	v_pk_mul_f32 v[70:71], v[48:49], v[48:49]
	v_add_f32_e32 v14, v69, v14
	v_pk_add_f32 v[50:51], v[50:51], v[52:53] op_sel_hi:[1,0] neg_lo:[0,1] neg_hi:[0,1]
	v_add_f32_e32 v14, v70, v14
	v_pk_mul_f32 v[52:53], v[50:51], v[50:51]
	v_add_f32_e32 v14, v71, v14
	v_add_f32_e32 v14, v52, v14
	v_add_f32_e32 v14, v53, v14
	ds_bpermute_b32 v15, v215, v14
	s_waitcnt lgkmcnt(0)
	v_add_f32_e32 v14, v14, v15
	ds_bpermute_b32 v15, v214, v14
	s_waitcnt lgkmcnt(0)
	v_add_f32_e32 v14, v14, v15
	s_waitcnt lgkmcnt(0)
	s_nop 1
	v_add_f32_dpp v14, v14, v14 row_ror:8 row_mask:0xf bank_mask:0xf
	s_waitcnt lgkmcnt(0)
	s_nop 1
	v_mov_b32_dpp v15, v14 row_half_mirror row_mask:0xf bank_mask:0xf
	s_nop 1
	v_add_f32_dpp v14, v15, v14 quad_perm:[3,2,1,0] row_mask:0xf bank_mask:0xf
	s_waitcnt lgkmcnt(0)
	s_nop 1
	v_add_f32_dpp v14, v14, v14 quad_perm:[2,3,0,1] row_mask:0xf bank_mask:0xf
	s_waitcnt lgkmcnt(0)
	s_nop 1
	v_add_f32_dpp v14, v14, v14 quad_perm:[1,0,3,2] row_mask:0xf bank_mask:0xf
	v_fmamk_f32 v14, v14, 0x3a800000, v201
	v_cmp_gt_f32_e32 vcc, s62, v14
	v_mul_f32_e32 v15, 0x4b800000, v14
	s_nop 0
	v_cndmask_b32_e32 v14, v14, v15, vcc
	v_rsq_f32_e32 v14, v14
	s_nop 0
	v_mul_f32_e32 v15, 0x45800000, v14
	v_cndmask_b32_e32 v52, v14, v15, vcc
	v_pk_mul_f32 v[14:15], v[16:17], v[52:53] op_sel_hi:[1,0]
	s_and_b64 vcc, exec, s[30:31]
	v_pk_fma_f32 v[14:15], v[2:3], v[14:15], v[6:7]
	v_pk_mul_f32 v[2:3], v[60:61], v[52:53] op_sel_hi:[1,0]
	s_nop 0
	v_pk_fma_f32 v[16:17], v[4:5], v[2:3], v[8:9]
	v_pk_mul_f32 v[2:3], v[44:45], v[52:53] op_sel_hi:[1,0]
	v_pk_mul_f32 v[4:5], v[50:51], v[52:53] op_sel_hi:[1,0]
	v_pk_fma_f32 v[10:11], v[10:11], v[2:3], v[18:19]
	v_pk_mul_f32 v[2:3], v[42:43], v[52:53] op_sel_hi:[1,0]
	s_waitcnt vmcnt(0)
	v_pk_fma_f32 v[4:5], v[32:33], v[4:5], v[36:37]
	v_pk_fma_f32 v[12:13], v[12:13], v[2:3], v[20:21]
	v_pk_mul_f32 v[2:3], v[56:57], v[52:53] op_sel_hi:[1,0]
	s_nop 0
	v_pk_fma_f32 v[6:7], v[22:23], v[2:3], v[26:27]
	v_pk_mul_f32 v[2:3], v[58:59], v[52:53] op_sel_hi:[1,0]
	s_nop 0
	v_pk_fma_f32 v[8:9], v[24:25], v[2:3], v[28:29]
	v_pk_mul_f32 v[2:3], v[48:49], v[52:53] op_sel_hi:[1,0]
	s_nop 0
	v_pk_fma_f32 v[2:3], v[30:31], v[2:3], v[34:35]
	s_cbranch_vccz .LBB0_873
	v_add_f32_e32 v18, 0, v14
	v_add_f32_e32 v18, v15, v18
	v_add_f32_e32 v18, v16, v18
	v_add_f32_e32 v18, v17, v18
	v_add_f32_e32 v18, v10, v18
	v_add_f32_e32 v18, v11, v18
	v_add_f32_e32 v18, v12, v18
	v_add_f32_e32 v18, v13, v18
	v_add_f32_e32 v18, v6, v18
	v_add_f32_e32 v18, v7, v18
	v_add_f32_e32 v18, v8, v18
	v_add_f32_e32 v18, v9, v18
	v_add_f32_e32 v18, v2, v18
	v_add_f32_e32 v18, v3, v18
	v_add_f32_e32 v18, v4, v18
	v_add_f32_e32 v18, v5, v18
	ds_bpermute_b32 v19, v215, v18
	v_add_u32_e32 v22, 3, v46
	global_store_dwordx4 v[40:41], v[14:17], off
	global_store_dwordx4 v[40:41], v[10:13], off offset:1024
	s_waitcnt lgkmcnt(0)
	v_add_f32_e32 v20, v18, v19
	ds_bpermute_b32 v21, v214, v20
	v_mov_b64_e32 v[18:19], s[16:17]
	v_mad_u64_u32 v[18:19], s[0:1], v22, s63, v[18:19]
	v_lshl_add_u64 v[48:49], v[18:19], 0, v[0:1]
	s_waitcnt lgkmcnt(0)
	v_add_f32_e32 v20, v20, v21
	v_add_co_u32_e32 v18, vcc, s58, v48
	s_mov_b64 s[0:1], 0x1000
	s_nop 0
	v_addc_co_u32_e32 v19, vcc, 0, v49, vcc
	s_waitcnt lgkmcnt(0)
	s_nop 1
	v_add_f32_dpp v0, v20, v20 row_ror:8 row_mask:0xf bank_mask:0xf
	v_lshl_add_u64 v[30:31], v[48:49], 0, s[0:1]
	global_load_dwordx4 v[18:21], v[18:19], off
	s_nop 0
	global_load_dwordx4 v[22:25], v[30:31], off offset:1024
	s_nop 0
	global_store_dwordx4 v[40:41], v[6:9], off offset:2048
	global_store_dwordx4 v[40:41], v[2:5], off offset:3072
	s_mov_b64 s[0:1], 0
	s_waitcnt lgkmcnt(0)
	s_nop 1
	v_mov_b32_dpp v26, v0 row_half_mirror row_mask:0xf bank_mask:0xf
	s_nop 1
	v_add_f32_dpp v0, v26, v0 quad_perm:[3,2,1,0] row_mask:0xf bank_mask:0xf
	s_waitcnt lgkmcnt(0)
	s_nop 1
	v_add_f32_dpp v0, v0, v0 quad_perm:[2,3,0,1] row_mask:0xf bank_mask:0xf
	global_load_dwordx4 v[26:29], v[30:31], off offset:2048
	s_nop 0
	global_load_dwordx4 v[30:33], v[30:31], off offset:3072
	s_nop 0
	global_load_dwordx4 v[34:37], v[48:49], off
	global_load_dwordx4 v[40:43], v[48:49], off offset:1024
	s_waitcnt lgkmcnt(0)
	s_nop 1
	v_add_f32_dpp v0, v0, v0 quad_perm:[1,0,3,2] row_mask:0xf bank_mask:0xf
	global_load_dwordx4 v[44:47], v[48:49], off offset:2048
	v_mul_f32_e32 v0, 0x3a800000, v0
	global_load_dwordx4 v[48:51], v[48:49], off offset:3072
	v_pk_add_f32 v[54:55], v[14:15], v[0:1] op_sel_hi:[1,0] neg_lo:[0,1] neg_hi:[0,1]
	v_pk_add_f32 v[52:53], v[16:17], v[0:1] op_sel_hi:[1,0] neg_lo:[0,1] neg_hi:[0,1]
	v_pk_mul_f32 v[60:61], v[54:55], v[54:55]
	v_pk_add_f32 v[56:57], v[12:13], v[0:1] op_sel_hi:[1,0] neg_lo:[0,1] neg_hi:[0,1]
	v_pk_mul_f32 v[58:59], v[52:53], v[52:53]
	v_pk_add_f32 v[64:65], v[10:11], v[0:1] op_sel_hi:[1,0] neg_lo:[0,1] neg_hi:[0,1]
	v_pk_add_f32 v[68:69], v[8:9], v[0:1] op_sel_hi:[1,0] neg_lo:[0,1] neg_hi:[0,1]
	v_pk_add_f32 v[72:73], v[6:7], v[0:1] op_sel_hi:[1,0] neg_lo:[0,1] neg_hi:[0,1]
	v_pk_add_f32 v[76:77], v[4:5], v[0:1] op_sel_hi:[1,0] neg_lo:[0,1] neg_hi:[0,1]
	v_pk_add_f32 v[80:81], v[2:3], v[0:1] op_sel_hi:[1,0] neg_lo:[0,1] neg_hi:[0,1]
	v_add_f32_e32 v0, v60, v61
	v_add_f32_e32 v0, v58, v0
	v_pk_mul_f32 v[66:67], v[64:65], v[64:65]
	v_add_f32_e32 v0, v59, v0
	v_add_f32_e32 v0, v66, v0
	v_pk_mul_f32 v[62:63], v[56:57], v[56:57]
	v_add_f32_e32 v0, v67, v0
	v_add_f32_e32 v0, v62, v0
	v_pk_mul_f32 v[74:75], v[72:73], v[72:73]
	v_add_f32_e32 v0, v63, v0
	v_add_f32_e32 v0, v74, v0
	v_pk_mul_f32 v[70:71], v[68:69], v[68:69]
	v_add_f32_e32 v0, v75, v0
	v_add_f32_e32 v0, v70, v0
	v_pk_mul_f32 v[82:83], v[80:81], v[80:81]
	v_add_f32_e32 v0, v71, v0
	v_add_f32_e32 v0, v82, v0
	v_pk_mul_f32 v[78:79], v[76:77], v[76:77]
	v_add_f32_e32 v0, v83, v0
	v_add_f32_e32 v0, v78, v0
	v_add_f32_e32 v0, v79, v0
	ds_bpermute_b32 v58, v215, v0
	s_waitcnt lgkmcnt(0)
	v_add_f32_e32 v0, v0, v58
	ds_bpermute_b32 v58, v214, v0
	s_waitcnt lgkmcnt(0)
	v_add_f32_e32 v0, v0, v58
	s_waitcnt lgkmcnt(0)
	s_nop 1
	v_add_f32_dpp v0, v0, v0 row_ror:8 row_mask:0xf bank_mask:0xf
	s_waitcnt lgkmcnt(0)
	s_nop 1
	v_mov_b32_dpp v58, v0 row_half_mirror row_mask:0xf bank_mask:0xf
	s_nop 1
	v_add_f32_dpp v0, v58, v0 quad_perm:[3,2,1,0] row_mask:0xf bank_mask:0xf
	s_waitcnt lgkmcnt(0)
	s_nop 1
	v_add_f32_dpp v0, v0, v0 quad_perm:[2,3,0,1] row_mask:0xf bank_mask:0xf
	s_waitcnt vmcnt(9)
	v_pk_add_f32 v[18:19], v[18:19], 1.0 op_sel_hi:[1,0]
	v_pk_add_f32 v[20:21], v[20:21], 1.0 op_sel_hi:[1,0]
	s_waitcnt vmcnt(8)
	v_pk_add_f32 v[22:23], v[22:23], 1.0 op_sel_hi:[1,0]
	v_pk_add_f32 v[24:25], v[24:25], 1.0 op_sel_hi:[1,0]
	s_waitcnt lgkmcnt(0)
	s_nop 1
	v_add_f32_dpp v0, v0, v0 quad_perm:[1,0,3,2] row_mask:0xf bank_mask:0xf
	v_fmamk_f32 v0, v0, 0x3a800000, v201
	v_mul_f32_e32 v58, 0x4b800000, v0
	v_cmp_gt_f32_e32 vcc, s62, v0
	s_waitcnt vmcnt(5)
	v_pk_add_f32 v[28:29], v[28:29], 1.0 op_sel_hi:[1,0]
	s_waitcnt vmcnt(4)
	v_pk_add_f32 v[30:31], v[30:31], 1.0 op_sel_hi:[1,0]
	v_cndmask_b32_e32 v0, v0, v58, vcc
	v_rsq_f32_e32 v0, v0
	v_pk_add_f32 v[32:33], v[32:33], 1.0 op_sel_hi:[1,0]
	v_pk_add_f32 v[26:27], v[26:27], 1.0 op_sel_hi:[1,0]
	v_mul_f32_e32 v58, 0x45800000, v0
	v_cndmask_b32_e32 v0, v0, v58, vcc
	v_pk_mul_f32 v[54:55], v[54:55], v[0:1] op_sel_hi:[1,0]
	v_pk_mul_f32 v[52:53], v[52:53], v[0:1] op_sel_hi:[1,0]
	s_waitcnt vmcnt(3)
	v_pk_fma_f32 v[18:19], v[18:19], v[54:55], v[34:35]
	v_pk_mul_f32 v[34:35], v[68:69], v[0:1] op_sel_hi:[1,0]
	v_pk_mul_f32 v[58:59], v[64:65], v[0:1] op_sel_hi:[1,0]
	s_waitcnt vmcnt(1)
	v_pk_fma_f32 v[28:29], v[34:35], v[28:29], v[46:47]
	v_pk_mul_f32 v[34:35], v[80:81], v[0:1] op_sel_hi:[1,0]
	v_pk_mul_f32 v[56:57], v[56:57], v[0:1] op_sel_hi:[1,0]
	v_pk_fma_f32 v[20:21], v[20:21], v[52:53], v[36:37]
	s_waitcnt vmcnt(0)
	v_pk_fma_f32 v[30:31], v[34:35], v[30:31], v[48:49]
	v_pk_mul_f32 v[34:35], v[76:77], v[0:1] op_sel_hi:[1,0]
	v_pk_mul_f32 v[60:61], v[72:73], v[0:1] op_sel_hi:[1,0]
	v_pk_fma_f32 v[22:23], v[22:23], v[58:59], v[40:41]
	v_pk_fma_f32 v[24:25], v[24:25], v[56:57], v[42:43]
	v_pk_fma_f32 v[32:33], v[34:35], v[32:33], v[50:51]
	v_lshl_add_u64 v[34:35], v[38:39], 1, v[138:139]
	v_cvt_pk_bf16_f32 v18, v18, v19
	v_cvt_pk_bf16_f32 v19, v20, v21
	v_pk_fma_f32 v[26:27], v[26:27], v[60:61], v[44:45]
	global_store_dwordx2 v[34:35], v[18:19], off
	v_cvt_pk_bf16_f32 v18, v22, v23
	v_cvt_pk_bf16_f32 v19, v24, v25
	global_store_dwordx2 v[34:35], v[18:19], off offset:512
	v_cvt_pk_bf16_f32 v18, v26, v27
	v_cvt_pk_bf16_f32 v19, v28, v29
	global_store_dwordx2 v[34:35], v[18:19], off offset:1024
	v_cvt_pk_bf16_f32 v18, v30, v31
	v_cvt_pk_bf16_f32 v19, v32, v33
	global_store_dwordx2 v[34:35], v[18:19], off offset:1536
